# producer preparation split deeper for two of the four slots (170 instead of 100 instructions run one interval early)
# speedup vs baseline: 1.0783x; 1.0018x over previous
.LBB0_1141:
	s_or_b64 exec, exec, s[38:39]
	s_mov_b64 s[98:99], exec
	s_andn2_b64 exec, exec, s[14:15]
	s_cbranch_execz .Lh1skip1
	s_waitcnt vmcnt(2)
	v_lshlrev_b32_e32 v13, 16, v72
	v_and_b32_e32 v15, 0xffff0000, v72
	v_lshlrev_b32_e32 v105, 16, v73
	v_lshlrev_b32_e32 v104, 16, v69
	v_and_b32_e32 v107, 0xffff0000, v73
	v_and_b32_e32 v106, 0xffff0000, v69
	v_add_f32_e32 v121, -1.0, v106
	v_mov_b32_e32 v120, v107
	v_add_f32_e32 v117, -1.0, v104
	v_mov_b32_e32 v112, v13
	v_mov_b32_e32 v113, v15
	v_mov_b32_e32 v116, v105
	v_pk_mul_f32 v[118:119], v[44:45], v[120:121]
	v_pk_mul_f32 v[122:123], v[0:1], v[112:113]
	v_pk_mul_f32 v[124:125], v[46:47], v[116:117]
	v_pk_mul_f32 v[112:113], v[122:123], v[122:123]
	v_mov_b32_e32 v114, v118
	v_mov_b32_e32 v115, v124
	v_pk_mul_f32 v[114:115], v[114:115], v[114:115]
	v_add_f32_e32 v12, v112, v113
	v_add_f32_e32 v12, v12, v115
	v_add_f32_e32 v12, v114, v12
	s_waitcnt vmcnt(0)
	v_lshlrev_b32_e32 v110, 16, v74
	v_and_b32_e32 v111, 0xffff0000, v74
	v_add_f32_dpp v12, v12, v12 quad_perm:[1,0,3,2] row_mask:0xf bank_mask:0xf bound_ctrl:1
	v_lshlrev_b32_e32 v108, 16, v75
	v_and_b32_e32 v109, 0xffff0000, v75
	v_add_f32_dpp v12, v12, v12 quad_perm:[2,3,0,1] row_mask:0xf bank_mask:0xf bound_ctrl:1
	s_nop 1
	v_add_f32_dpp v12, v12, v12 row_ror:4 row_mask:0xf bank_mask:0xf bound_ctrl:1
	s_nop 1
	v_add_f32_dpp v12, v12, v12 row_ror:8 row_mask:0xf bank_mask:0xf bound_ctrl:1
	v_mul_f32_e32 v14, 0x4f800000, v12
	v_cmp_gt_f32_e32 vcc, s42, v12
	s_nop 1
	v_cndmask_b32_e32 v22, v12, v14, vcc
	v_sqrt_f32_e32 v42, v22
	v_lshlrev_b32_e32 v12, 16, v68
	v_and_b32_e32 v14, 0xffff0000, v68
	v_add_f32_e32 v112, -1.0, v12
	v_add_u32_e32 v113, -1, v42
	v_fma_f32 v114, -v113, v42, v22
	v_cmp_ge_f32_e64 s[16:17], 0, v114
	v_add_u32_e32 v114, 1, v42
	s_nop 0
	v_cndmask_b32_e64 v113, v42, v113, s[16:17]
	v_fma_f32 v42, -v114, v42, v22
	v_cmp_lt_f32_e64 s[16:17], 0, v42
	s_nop 1
	v_cndmask_b32_e64 v42, v113, v114, s[16:17]
	v_mul_f32_e32 v113, 0x37800000, v42
	v_cndmask_b32_e32 v42, v42, v113, vcc
	v_cmp_class_f32_e32 vcc, v22, v149
	v_fma_f32 v113, v4, v112, 1.0
	v_add_f32_e32 v112, -1.0, v14
	v_cndmask_b32_e32 v22, v42, v22, vcc
	v_max_f32_e32 v22, 0x2b8cbccc, v22
	v_div_scale_f32 v42, s[16:17], v22, v22, 1.0
	v_rcp_f32_e32 v114, v42
	v_fma_f32 v115, v5, v112, 1.0
	v_fma_f32 v112, -v42, v114, 1.0
	v_fmac_f32_e32 v114, v112, v114
	v_div_scale_f32 v112, vcc, 1.0, v22, 1.0
	v_mul_f32_e32 v126, v112, v114
	v_fma_f32 v127, -v42, v126, v112
	v_fmac_f32_e32 v126, v127, v114
	v_fma_f32 v42, -v42, v126, v112
	v_div_fmas_f32 v42, v42, v114, v126
	v_div_fixup_f32 v42, v42, v22, 1.0
	v_mul_f32_e32 v112, v122, v42
	v_mul_f32_e32 v114, v123, v42
	v_pk_mul_f32 v[112:113], v[112:113], v[12:13]
	v_pk_mul_f32 v[114:115], v[114:115], v[14:15]
	v_pk_mul_f32 v[12:13], v[124:125], v[42:43]
	v_pk_fma_f32 v[14:15], v[46:47], v[116:117], s[2:3]
	v_pk_mul_f32 v[126:127], v[112:113], v[110:111] op_sel:[1,0] op_sel_hi:[0,1]
	v_mov_b32_e32 v13, v15
	v_pk_mul_f32 v[116:117], v[12:13], v[104:105]
	v_pk_mul_f32 v[12:13], v[118:119], v[42:43]
	v_pk_fma_f32 v[14:15], v[44:45], v[120:121], s[2:3]
	v_fma_f32 v22, v8, v126, 0
	v_pk_mul_f32 v[128:129], v[114:115], v[110:111]
	v_mov_b32_e32 v13, v15
	v_fmac_f32_e32 v22, v9, v129
	v_pk_mul_f32 v[134:135], v[116:117], v[108:109] op_sel:[1,0] op_sel_hi:[0,1]
	v_pk_mul_f32 v[120:121], v[12:13], v[106:107]
	v_fmac_f32_e32 v22, v10, v134
	v_pk_mul_f32 v[136:137], v[120:121], v[108:109]
	s_nop 0
	v_fmac_f32_e32 v22, v11, v137
	s_nop 1
	v_add_f32_dpp v12, v22, v22 quad_perm:[1,0,3,2] row_mask:0xf bank_mask:0xf bound_ctrl:1
	s_nop 1
	v_add_f32_dpp v12, v12, v12 quad_perm:[2,3,0,1] row_mask:0xf bank_mask:0xf bound_ctrl:1
	s_nop 1
	v_add_f32_dpp v12, v12, v12 row_ror:4 row_mask:0xf bank_mask:0xf bound_ctrl:1
	s_nop 1
	v_mov_b32_dpp v13, v12 row_ror:8 row_mask:0xf bank_mask:0xf bound_ctrl:1
	s_and_saveexec_b64 s[16:17], s[8:9]
	s_cbranch_execz .LBB0_1146
	v_lshl_add_u64 v[14:15], s[84:85], 0, v[66:67]
	v_add_f32_e32 v12, v12, v13
	global_store_dword v[14:15], v12, off offset:-1024

.LBB0_1148:
	s_or_b64 exec, exec, s[16:17]
	v_add_f32_e32 v22, v22, v119
	v_mul_f32_e32 v119, 0x4f800000, v22
	v_cmp_gt_f32_e32 vcc, s42, v22
	v_cvt_f32_f16_e32 v125, v96
	v_cvt_f32_f16_sdwa v127, v96 dst_sel:DWORD dst_unused:UNUSED_PAD src0_sel:WORD_1
	v_cndmask_b32_e32 v22, v22, v119, vcc
	v_sqrt_f32_e32 v119, v22
	v_cvt_f32_f16_e32 v128, v97
	v_mul_f32_e32 v125, 0xbfb8aa3b, v125
	v_exp_f32_e32 v168, v125
	v_mul_f32_e32 v125, 0xbfb8aa3b, v127
	v_add_u32_e32 v127, -1, v119
.Lh1skip1:
	s_mov_b64 exec, s[98:99]
	s_waitcnt lgkmcnt(0)
	s_barrier
	v_lshl_add_u64 v[102:103], s[84:85], 0, v[60:61]
	v_lshl_add_u64 v[100:101], s[84:85], 0, v[62:63]
	s_and_saveexec_b64 s[16:17], s[14:15]
	s_xor_b64 s[16:17], exec, s[16:17]
	s_cbranch_execz .LBB0_1143
	ds_read_b128 v[12:15], v146 offset:39936
	ds_read_b128 v[104:107], v146 offset:39952
	ds_read_b128 v[108:111], v146 offset:39968
	ds_read_b128 v[112:115], v146 offset:39984
	s_mov_b32 s38, 0x3018000
	s_waitcnt lgkmcnt(3)
	v_add_f32_e32 v12, v12, v13
	v_add_f32_e32 v13, v14, v15
	v_add_f32_e32 v12, v12, v13
	s_waitcnt lgkmcnt(2)
	v_add_f32_e32 v13, v104, v105
	v_add_f32_e32 v14, v106, v107
	v_add_f32_e32 v13, v13, v14
	v_add_f32_e32 v12, v12, v13
	s_waitcnt lgkmcnt(1)
	v_add_f32_e32 v13, v108, v109
	v_add_f32_e32 v14, v110, v111
	v_add_f32_e32 v13, v13, v14
	v_add_f32_e32 v12, v12, v13
	s_waitcnt lgkmcnt(0)
	v_add_f32_e32 v13, v112, v113
	v_add_f32_e32 v14, v114, v115
	v_add_f32_e32 v13, v13, v14
	v_add_f32_e32 v12, v12, v13
	v_bfe_u32 v13, v12, 16, 1
	v_add3_u32 v22, v12, v13, s41
	v_add_co_u32_e32 v104, vcc, s38, v102
	ds_read_b128 v[12:15], v147 offset:39936
	s_nop 0
	v_addc_co_u32_e32 v105, vcc, 0, v103, vcc
	global_store_short_d16_hi v[104:105], v22, off
	ds_read_b128 v[104:107], v147 offset:39952
	ds_read_b128 v[108:111], v147 offset:39968
	ds_read_b128 v[112:115], v147 offset:39984
	s_waitcnt lgkmcnt(3)
	v_add_f32_e32 v12, v12, v13
	v_add_f32_e32 v13, v14, v15
	v_add_f32_e32 v12, v12, v13
	s_waitcnt lgkmcnt(2)
	v_add_f32_e32 v13, v104, v105
	v_add_f32_e32 v14, v106, v107
	v_add_f32_e32 v13, v13, v14
	v_add_f32_e32 v12, v12, v13
	s_waitcnt lgkmcnt(1)
	v_add_f32_e32 v13, v108, v109
	v_add_f32_e32 v14, v110, v111
	v_add_f32_e32 v13, v13, v14
	v_add_f32_e32 v12, v12, v13
	s_waitcnt lgkmcnt(0)
	v_add_f32_e32 v13, v112, v113
	v_add_f32_e32 v14, v114, v115
	v_add_f32_e32 v13, v13, v14
	v_add_f32_e32 v12, v12, v13
	v_bfe_u32 v13, v12, 16, 1
	v_add3_u32 v14, v12, v13, s41
	v_add_co_u32_e32 v12, vcc, 0x3018000, v100
	s_nop 1
	v_addc_co_u32_e32 v13, vcc, 0, v101, vcc
	global_store_short_d16_hi v[12:13], v14, off
.LBB0_1143:
	s_andn2_saveexec_b64 s[38:39], s[16:17]
	s_cbranch_execz .LBB0_1152
	v_exp_f32_e32 v169, v125
	v_mul_f32_e32 v125, 0xbfb8aa3b, v128
	v_fma_f32 v128, -v127, v119, v22
	v_cmp_ge_f32_e64 s[16:17], 0, v128
	v_add_u32_e32 v128, 1, v119
	v_cvt_f32_f16_sdwa v135, v97 dst_sel:DWORD dst_unused:UNUSED_PAD src0_sel:WORD_1
	v_cndmask_b32_e64 v127, v119, v127, s[16:17]
	v_fma_f32 v119, -v128, v119, v22
	v_cmp_lt_f32_e64 s[16:17], 0, v119
	v_exp_f32_e32 v170, v125
	v_mul_f32_e32 v125, 0xbfb8aa3b, v135
	v_cndmask_b32_e64 v119, v127, v128, s[16:17]
	v_mul_f32_e32 v127, 0x37800000, v119
	v_cndmask_b32_e32 v119, v119, v127, vcc
	v_cmp_class_f32_e32 vcc, v22, v149
	v_exp_f32_e32 v171, v125
	v_pk_mul_f32 v[178:179], v[120:121], v[108:109] op_sel:[0,1] op_sel_hi:[1,0]
	v_cndmask_b32_e32 v22, v119, v22, vcc
	v_max_f32_e32 v22, 0x2b8cbccc, v22
	v_div_scale_f32 v119, s[16:17], v22, v22, 1.0
	v_rcp_f32_e32 v127, v119
	v_mov_b32_e32 v179, v137
	v_pk_mul_f32 v[136:137], v[170:171], v[116:117] op_sel_hi:[0,1]
	v_fma_f32 v125, -v119, v127, 1.0
	v_fmac_f32_e32 v127, v125, v127
	v_div_scale_f32 v125, vcc, 1.0, v22, 1.0
	v_mul_f32_e32 v128, v125, v127
	v_fma_f32 v135, -v119, v128, v125
	v_fmac_f32_e32 v128, v135, v127
	v_fma_f32 v119, -v119, v128, v125
	v_div_fmas_f32 v119, v119, v127, v128
	v_div_fixup_f32 v22, v119, v22, 1.0
	v_pk_mul_f32 v[152:153], v[142:143], v[22:23] op_sel_hi:[1,0]
	v_pk_mul_f32 v[172:173], v[22:23], v[142:143] op_sel_hi:[0,1] neg_lo:[0,1] neg_hi:[0,1]
	v_pk_mul_f32 v[142:143], v[144:145], v[22:23] op_sel_hi:[1,0]
	v_pk_mul_f32 v[144:145], v[22:23], v[144:145] op_sel_hi:[0,1] neg_lo:[0,1] neg_hi:[0,1]
	v_cvt_f32_f16_e32 v22, v84
	v_cvt_f32_f16_sdwa v119, v84 dst_sel:DWORD dst_unused:UNUSED_PAD src0_sel:WORD_1
	v_cvt_f32_f16_e32 v125, v85
	v_cvt_f32_f16_sdwa v127, v85 dst_sel:DWORD dst_unused:UNUSED_PAD src0_sel:WORD_1
	v_mul_f32_e32 v22, 0xbfb8aa3b, v22
	v_pk_mul_f32 v[142:143], v[142:143], v[138:139]
	v_exp_f32_e32 v138, v22
	v_mul_f32_e32 v22, 0xbfb8aa3b, v119
	v_exp_f32_e32 v139, v22
	v_mul_f32_e32 v22, 0xbfb8aa3b, v125
	v_exp_f32_e32 v166, v22
	v_mul_f32_e32 v22, 0xbfb8aa3b, v127
	v_exp_f32_e32 v167, v22
	v_mov_b32_e32 v125, v118
	v_pk_mul_f32 v[118:119], v[112:113], v[110:111]
	v_pk_mul_f32 v[140:141], v[152:153], v[140:141]
	v_pk_mul_f32 v[152:153], v[42:43], v[122:123] op_sel_hi:[0,1] neg_lo:[0,1] neg_hi:[0,1]
	v_pk_mul_f32 v[154:155], v[42:43], v[124:125] op_sel_hi:[0,1] neg_lo:[0,1] neg_hi:[0,1]
	v_pk_mul_f32 v[122:123], v[114:115], v[110:111] op_sel:[0,1] op_sel_hi:[1,0]
	v_pk_mul_f32 v[158:159], v[166:167], v[144:145]
	v_pk_mul_f32 v[162:163], v[170:171], v[166:167]
	v_pk_mul_f32 v[166:167], v[166:167], v[108:109]
	v_pk_mul_f32 v[124:125], v[116:117], v[108:109]
	v_pk_fma_f32 v[108:109], v[112:113], v[172:173], 0 op_sel_hi:[1,0,0]
	v_mov_b32_e32 v119, v126
	v_pk_mul_f32 v[156:157], v[138:139], v[172:173]
	v_pk_mul_f32 v[160:161], v[168:169], v[138:139]
	v_pk_mul_f32 v[164:165], v[138:139], v[110:111]
	v_pk_mul_f32 v[138:139], v[140:141], v[104:105]
	v_pk_fma_f32 v[108:109], v[114:115], v[172:173], v[108:109] op_sel:[0,1,0]
	v_pk_add_f32 v[118:119], v[118:119], 0 op_sel_hi:[1,0]
	v_mov_b32_e32 v123, v129
	v_pk_fma_f32 v[108:109], v[116:117], v[144:145], v[108:109] op_sel_hi:[1,0,1]
	v_pk_add_f32 v[118:119], v[122:123], v[118:119]
	v_mov_b32_e32 v125, v134
	v_pk_mul_f32 v[134:135], v[168:169], v[112:113] op_sel_hi:[0,1]
	v_mov_b32_e32 v22, v169
	v_mov_b32_e32 v116, v138
	v_mov_b32_e32 v117, v130
	v_pk_mul_f32 v[176:177], v[142:143], v[106:107]
	v_pk_add_f32 v[118:119], v[124:125], v[118:119]
	v_pk_fma_f32 v[112:113], v[134:135], v[104:105], 0 op_sel_hi:[1,0,0]
	v_pk_mul_f32 v[124:125], v[22:23], v[114:115] op_sel_hi:[0,1]
	v_mov_b32_e32 v22, v171
	v_pk_add_f32 v[116:117], v[116:117], 0 op_sel_hi:[1,0]
	v_mov_b32_e32 v130, v139
	v_pk_fma_f32 v[108:109], v[120:121], v[144:145], v[108:109] op_sel:[0,1,0]
	v_pk_fma_f32 v[112:113], v[124:125], v[104:105], v[112:113] op_sel:[0,1,0]
	v_pk_mul_f32 v[126:127], v[22:23], v[120:121] op_sel_hi:[0,1]
	v_pk_add_f32 v[116:117], v[130:131], v[116:117]
	v_mov_b32_e32 v120, v176
	v_mov_b32_e32 v121, v132
	v_pk_fma_f32 v[112:113], v[136:137], v[106:107], v[112:113] op_sel_hi:[1,0,1]
	v_pk_add_f32 v[116:117], v[120:121], v[116:117]
	v_mov_b32_e32 v132, v177
	v_pk_add_f32 v[118:119], v[178:179], v[118:119]
	v_pk_fma_f32 v[112:113], v[126:127], v[106:107], v[112:113] op_sel:[0,1,0]
	v_pk_add_f32 v[116:117], v[132:133], v[116:117]
	v_mov_b32_dpp v110, v108 quad_perm:[1,0,3,2] row_mask:0xf bank_mask:0xf bound_ctrl:1
	v_mov_b32_dpp v111, v109 quad_perm:[1,0,3,2] row_mask:0xf bank_mask:0xf bound_ctrl:1
	v_mov_b32_dpp v122, v118 quad_perm:[1,0,3,2] row_mask:0xf bank_mask:0xf bound_ctrl:1
	v_mov_b32_dpp v123, v119 quad_perm:[1,0,3,2] row_mask:0xf bank_mask:0xf bound_ctrl:1
	v_mov_b32_dpp v114, v112 quad_perm:[1,0,3,2] row_mask:0xf bank_mask:0xf bound_ctrl:1
	v_mov_b32_dpp v115, v113 quad_perm:[1,0,3,2] row_mask:0xf bank_mask:0xf bound_ctrl:1
	v_mov_b32_dpp v120, v116 quad_perm:[1,0,3,2] row_mask:0xf bank_mask:0xf bound_ctrl:1
	v_mov_b32_dpp v121, v117 quad_perm:[1,0,3,2] row_mask:0xf bank_mask:0xf bound_ctrl:1
	v_pk_add_f32 v[108:109], v[108:109], v[110:111]
	v_pk_add_f32 v[118:119], v[118:119], v[122:123]
	v_pk_add_f32 v[112:113], v[112:113], v[114:115]
	v_pk_add_f32 v[116:117], v[116:117], v[120:121]
	v_mov_b32_dpp v110, v108 quad_perm:[2,3,0,1] row_mask:0xf bank_mask:0xf bound_ctrl:1
	v_mov_b32_dpp v111, v109 quad_perm:[2,3,0,1] row_mask:0xf bank_mask:0xf bound_ctrl:1
	v_mov_b32_dpp v122, v118 quad_perm:[2,3,0,1] row_mask:0xf bank_mask:0xf bound_ctrl:1
	v_mov_b32_dpp v123, v119 quad_perm:[2,3,0,1] row_mask:0xf bank_mask:0xf bound_ctrl:1
	v_mov_b32_dpp v114, v112 quad_perm:[2,3,0,1] row_mask:0xf bank_mask:0xf bound_ctrl:1
	v_mov_b32_dpp v115, v113 quad_perm:[2,3,0,1] row_mask:0xf bank_mask:0xf bound_ctrl:1
	v_mov_b32_dpp v120, v116 quad_perm:[2,3,0,1] row_mask:0xf bank_mask:0xf bound_ctrl:1
	v_mov_b32_dpp v121, v117 quad_perm:[2,3,0,1] row_mask:0xf bank_mask:0xf bound_ctrl:1
	v_pk_add_f32 v[108:109], v[108:109], v[110:111]
	v_pk_add_f32 v[118:119], v[118:119], v[122:123]
	v_pk_add_f32 v[112:113], v[112:113], v[114:115]
	v_pk_add_f32 v[116:117], v[116:117], v[120:121]
	v_mov_b32_dpp v110, v108 row_ror:4 row_mask:0xf bank_mask:0xf bound_ctrl:1
	v_mov_b32_dpp v111, v109 row_ror:4 row_mask:0xf bank_mask:0xf bound_ctrl:1
	v_mov_b32_dpp v122, v118 row_ror:4 row_mask:0xf bank_mask:0xf bound_ctrl:1
	v_mov_b32_dpp v123, v119 row_ror:4 row_mask:0xf bank_mask:0xf bound_ctrl:1
	v_mov_b32_dpp v114, v112 row_ror:4 row_mask:0xf bank_mask:0xf bound_ctrl:1
	v_mov_b32_dpp v115, v113 row_ror:4 row_mask:0xf bank_mask:0xf bound_ctrl:1
	v_mov_b32_dpp v120, v116 row_ror:4 row_mask:0xf bank_mask:0xf bound_ctrl:1
	v_mov_b32_dpp v121, v117 row_ror:4 row_mask:0xf bank_mask:0xf bound_ctrl:1
	v_pk_add_f32 v[108:109], v[108:109], v[110:111]
	v_pk_add_f32 v[118:119], v[118:119], v[122:123]
	v_pk_add_f32 v[112:113], v[112:113], v[114:115]
	v_pk_add_f32 v[116:117], v[116:117], v[120:121]
	v_mov_b32_e32 v128, v134
	v_mov_b32_e32 v129, v124
	v_mov_b32_e32 v130, v136
	v_mov_b32_e32 v131, v126
	v_mov_b32_e32 v124, v135
	v_mov_b32_e32 v126, v137
	v_mov_b32_dpp v110, v108 row_ror:8 row_mask:0xf bank_mask:0xf bound_ctrl:1
	v_mov_b32_dpp v111, v109 row_ror:8 row_mask:0xf bank_mask:0xf bound_ctrl:1
	v_mov_b32_dpp v122, v118 row_ror:8 row_mask:0xf bank_mask:0xf bound_ctrl:1
	v_mov_b32_dpp v123, v119 row_ror:8 row_mask:0xf bank_mask:0xf bound_ctrl:1
	v_mov_b32_dpp v114, v112 row_ror:8 row_mask:0xf bank_mask:0xf bound_ctrl:1
	v_mov_b32_dpp v115, v113 row_ror:8 row_mask:0xf bank_mask:0xf bound_ctrl:1
	v_mov_b32_dpp v120, v116 row_ror:8 row_mask:0xf bank_mask:0xf bound_ctrl:1
	v_mov_b32_dpp v121, v117 row_ror:8 row_mask:0xf bank_mask:0xf bound_ctrl:1
	ds_write_b128 v29, v[152:155]
	ds_write_b128 v29, v[156:159] offset:256
	ds_write_b128 v29, v[160:163] offset:512
	ds_write_b128 v29, v[128:131] offset:768
	ds_write_b128 v29, v[124:127] offset:1024
	ds_write_b128 v29, v[140:143] offset:1280
	ds_write_b128 v29, v[12:15] offset:1536
	ds_write_b128 v29, v[164:167] offset:1792
	v_pk_mul_f32 v[12:13], v[160:161], v[104:105]
	v_pk_mul_f32 v[14:15], v[162:163], v[106:107]
	ds_write_b128 v29, v[12:15] offset:2048
	s_and_saveexec_b64 s[16:17], s[12:13]
	s_cbranch_execnz .LBB0_1180
	s_or_b64 exec, exec, s[16:17]
	s_and_saveexec_b64 s[16:17], s[4:5]
	s_cbranch_execnz .LBB0_1181

.LBB0_1152:
	s_or_b64 exec, exec, s[38:39]
	s_mov_b64 s[98:99], exec
	s_andn2_b64 exec, exec, s[6:7]
	s_cbranch_execz .Lh1skip2
	s_waitcnt vmcnt(2)
	v_lshlrev_b32_e32 v13, 16, v72
	v_and_b32_e32 v15, 0xffff0000, v72
	v_lshlrev_b32_e32 v105, 16, v73
	v_lshlrev_b32_e32 v104, 16, v69
	v_and_b32_e32 v107, 0xffff0000, v73
	v_and_b32_e32 v106, 0xffff0000, v69
	v_add_f32_e32 v121, -1.0, v106
	v_mov_b32_e32 v120, v107
	v_add_f32_e32 v117, -1.0, v104
	v_mov_b32_e32 v112, v13
	v_mov_b32_e32 v113, v15
	v_mov_b32_e32 v116, v105
	v_pk_mul_f32 v[118:119], v[44:45], v[120:121]
	v_pk_mul_f32 v[122:123], v[0:1], v[112:113]
	v_pk_mul_f32 v[124:125], v[46:47], v[116:117]
	v_pk_mul_f32 v[112:113], v[122:123], v[122:123]
	v_mov_b32_e32 v114, v118
	v_mov_b32_e32 v115, v124
	v_pk_mul_f32 v[114:115], v[114:115], v[114:115]
	v_add_f32_e32 v12, v112, v113
	v_add_f32_e32 v12, v12, v115
	v_add_f32_e32 v12, v114, v12
	s_waitcnt vmcnt(0)
	v_lshlrev_b32_e32 v110, 16, v74
	v_and_b32_e32 v111, 0xffff0000, v74
	v_add_f32_dpp v12, v12, v12 quad_perm:[1,0,3,2] row_mask:0xf bank_mask:0xf bound_ctrl:1
	v_lshlrev_b32_e32 v108, 16, v75
	v_and_b32_e32 v109, 0xffff0000, v75
	v_add_f32_dpp v12, v12, v12 quad_perm:[2,3,0,1] row_mask:0xf bank_mask:0xf bound_ctrl:1
	s_nop 1
	v_add_f32_dpp v12, v12, v12 row_ror:4 row_mask:0xf bank_mask:0xf bound_ctrl:1
	s_nop 1
	v_add_f32_dpp v12, v12, v12 row_ror:8 row_mask:0xf bank_mask:0xf bound_ctrl:1
	v_mul_f32_e32 v14, 0x4f800000, v12
	v_cmp_gt_f32_e32 vcc, s42, v12
	s_nop 1
	v_cndmask_b32_e32 v22, v12, v14, vcc
	v_sqrt_f32_e32 v42, v22
	v_lshlrev_b32_e32 v12, 16, v68
	v_and_b32_e32 v14, 0xffff0000, v68
	v_add_f32_e32 v112, -1.0, v12
	v_add_u32_e32 v113, -1, v42
	v_fma_f32 v114, -v113, v42, v22
	v_cmp_ge_f32_e64 s[16:17], 0, v114
	v_add_u32_e32 v114, 1, v42
	s_nop 0
	v_cndmask_b32_e64 v113, v42, v113, s[16:17]
	v_fma_f32 v42, -v114, v42, v22
	v_cmp_lt_f32_e64 s[16:17], 0, v42
	s_nop 1
	v_cndmask_b32_e64 v42, v113, v114, s[16:17]
	v_mul_f32_e32 v113, 0x37800000, v42
	v_cndmask_b32_e32 v42, v42, v113, vcc
	v_cmp_class_f32_e32 vcc, v22, v149
	v_fma_f32 v113, v4, v112, 1.0
	v_add_f32_e32 v112, -1.0, v14
	v_cndmask_b32_e32 v22, v42, v22, vcc
	v_max_f32_e32 v22, 0x2b8cbccc, v22
	v_div_scale_f32 v42, s[16:17], v22, v22, 1.0
	v_rcp_f32_e32 v114, v42
	v_fma_f32 v115, v5, v112, 1.0
	v_fma_f32 v112, -v42, v114, 1.0
	v_fmac_f32_e32 v114, v112, v114
	v_div_scale_f32 v112, vcc, 1.0, v22, 1.0
	v_mul_f32_e32 v126, v112, v114
	v_fma_f32 v127, -v42, v126, v112
	v_fmac_f32_e32 v126, v127, v114
	v_fma_f32 v42, -v42, v126, v112
	v_div_fmas_f32 v42, v42, v114, v126
	v_div_fixup_f32 v42, v42, v22, 1.0
	v_mul_f32_e32 v112, v122, v42
	v_mul_f32_e32 v114, v123, v42
	v_pk_mul_f32 v[112:113], v[112:113], v[12:13]
	v_pk_mul_f32 v[114:115], v[114:115], v[14:15]
	v_pk_mul_f32 v[12:13], v[124:125], v[42:43]
	v_pk_fma_f32 v[14:15], v[46:47], v[116:117], s[2:3]
	v_pk_mul_f32 v[126:127], v[112:113], v[110:111] op_sel:[1,0] op_sel_hi:[0,1]
	v_mov_b32_e32 v13, v15
	v_pk_mul_f32 v[116:117], v[12:13], v[104:105]
	v_pk_mul_f32 v[12:13], v[118:119], v[42:43]
	v_pk_fma_f32 v[14:15], v[44:45], v[120:121], s[2:3]
	v_fma_f32 v22, v8, v126, 0
	v_pk_mul_f32 v[128:129], v[114:115], v[110:111]
	v_mov_b32_e32 v13, v15
	v_fmac_f32_e32 v22, v9, v129
	v_pk_mul_f32 v[134:135], v[116:117], v[108:109] op_sel:[1,0] op_sel_hi:[0,1]
	v_pk_mul_f32 v[120:121], v[12:13], v[106:107]
	v_fmac_f32_e32 v22, v10, v134
	v_pk_mul_f32 v[136:137], v[120:121], v[108:109]
	s_nop 0
	v_fmac_f32_e32 v22, v11, v137
	s_nop 1
	v_add_f32_dpp v12, v22, v22 quad_perm:[1,0,3,2] row_mask:0xf bank_mask:0xf bound_ctrl:1
	s_nop 1
	v_add_f32_dpp v12, v12, v12 quad_perm:[2,3,0,1] row_mask:0xf bank_mask:0xf bound_ctrl:1
	s_nop 1
	v_add_f32_dpp v12, v12, v12 row_ror:4 row_mask:0xf bank_mask:0xf bound_ctrl:1
	s_nop 1
	v_mov_b32_dpp v13, v12 row_ror:8 row_mask:0xf bank_mask:0xf bound_ctrl:1
	s_and_saveexec_b64 s[16:17], s[8:9]
	s_cbranch_execz .LBB0_1157
	v_lshl_add_u64 v[14:15], s[84:85], 0, v[66:67]
	v_add_f32_e32 v12, v12, v13
	global_store_dword v[14:15], v12, off

.LBB0_1159:
	s_or_b64 exec, exec, s[16:17]
	v_add_f32_e32 v22, v22, v119
	v_mul_f32_e32 v119, 0x4f800000, v22
	v_cmp_gt_f32_e32 vcc, s42, v22
	v_cvt_f32_f16_e32 v125, v96
	v_cvt_f32_f16_sdwa v127, v96 dst_sel:DWORD dst_unused:UNUSED_PAD src0_sel:WORD_1
	v_cndmask_b32_e32 v22, v22, v119, vcc
	v_sqrt_f32_e32 v119, v22
	v_cvt_f32_f16_e32 v128, v97
	v_mul_f32_e32 v125, 0xbfb8aa3b, v125
	v_exp_f32_e32 v168, v125
	v_mul_f32_e32 v125, 0xbfb8aa3b, v127
.Lh1skip2:
	s_mov_b64 exec, s[98:99]
	s_waitcnt lgkmcnt(0)
	s_barrier
	s_and_saveexec_b64 s[16:17], s[6:7]
	s_xor_b64 s[16:17], exec, s[16:17]
	s_cbranch_execz .LBB0_1154
	ds_read_b128 v[12:15], v146 offset:56320
	ds_read_b128 v[104:107], v146 offset:56336
	ds_read_b128 v[108:111], v146 offset:56352
	ds_read_b128 v[112:115], v146 offset:56368
	s_mov_b32 s38, 0x3020000
	s_waitcnt lgkmcnt(3)
	v_add_f32_e32 v12, v12, v13
	v_add_f32_e32 v13, v14, v15
	v_add_f32_e32 v12, v12, v13
	s_waitcnt lgkmcnt(2)
	v_add_f32_e32 v13, v104, v105
	v_add_f32_e32 v14, v106, v107
	v_add_f32_e32 v13, v13, v14
	v_add_f32_e32 v12, v12, v13
	s_waitcnt lgkmcnt(1)
	v_add_f32_e32 v13, v108, v109
	v_add_f32_e32 v14, v110, v111
	v_add_f32_e32 v13, v13, v14
	v_add_f32_e32 v12, v12, v13
	s_waitcnt lgkmcnt(0)
	v_add_f32_e32 v13, v112, v113
	v_add_f32_e32 v14, v114, v115
	v_add_f32_e32 v13, v13, v14
	v_add_f32_e32 v12, v12, v13
	v_bfe_u32 v13, v12, 16, 1
	v_add3_u32 v22, v12, v13, s41
	v_add_co_u32_e32 v104, vcc, s38, v102
	ds_read_b128 v[12:15], v147 offset:56320
	s_nop 0
	v_addc_co_u32_e32 v105, vcc, 0, v103, vcc
	global_store_short_d16_hi v[104:105], v22, off offset:2048
	ds_read_b128 v[104:107], v147 offset:56336
	ds_read_b128 v[108:111], v147 offset:56352
	ds_read_b128 v[112:115], v147 offset:56368
	s_waitcnt lgkmcnt(3)
	v_add_f32_e32 v12, v12, v13
	v_add_f32_e32 v13, v14, v15
	v_add_f32_e32 v12, v12, v13
	s_waitcnt lgkmcnt(2)
	v_add_f32_e32 v13, v104, v105
	v_add_f32_e32 v14, v106, v107
	v_add_f32_e32 v13, v13, v14
	v_add_f32_e32 v12, v12, v13
	s_waitcnt lgkmcnt(1)
	v_add_f32_e32 v13, v108, v109
	v_add_f32_e32 v14, v110, v111
	v_add_f32_e32 v13, v13, v14
	v_add_f32_e32 v12, v12, v13
	s_waitcnt lgkmcnt(0)
	v_add_f32_e32 v13, v112, v113
	v_add_f32_e32 v14, v114, v115
	v_add_f32_e32 v13, v13, v14
	v_add_f32_e32 v12, v12, v13
	v_bfe_u32 v13, v12, 16, 1
	v_add3_u32 v14, v12, v13, s41
	v_add_co_u32_e32 v12, vcc, 0x3020000, v100
	s_nop 1
	v_addc_co_u32_e32 v13, vcc, 0, v101, vcc
	global_store_short_d16_hi v[12:13], v14, off offset:2048
.LBB0_1154:
	s_andn2_saveexec_b64 s[38:39], s[16:17]
	s_cbranch_execz .LBB0_1163
	v_add_u32_e32 v127, -1, v119
	v_exp_f32_e32 v169, v125
	v_mul_f32_e32 v125, 0xbfb8aa3b, v128
	v_fma_f32 v128, -v127, v119, v22
	v_cmp_ge_f32_e64 s[16:17], 0, v128
	v_add_u32_e32 v128, 1, v119
	v_cvt_f32_f16_sdwa v135, v97 dst_sel:DWORD dst_unused:UNUSED_PAD src0_sel:WORD_1
	v_cndmask_b32_e64 v127, v119, v127, s[16:17]
	v_fma_f32 v119, -v128, v119, v22
	v_cmp_lt_f32_e64 s[16:17], 0, v119
	v_exp_f32_e32 v170, v125
	v_mul_f32_e32 v125, 0xbfb8aa3b, v135
	v_cndmask_b32_e64 v119, v127, v128, s[16:17]
	v_mul_f32_e32 v127, 0x37800000, v119
	v_cndmask_b32_e32 v119, v119, v127, vcc
	v_cmp_class_f32_e32 vcc, v22, v149
	v_exp_f32_e32 v171, v125
	v_pk_mul_f32 v[178:179], v[120:121], v[108:109] op_sel:[0,1] op_sel_hi:[1,0]
	v_cndmask_b32_e32 v22, v119, v22, vcc
	v_max_f32_e32 v22, 0x2b8cbccc, v22
	v_div_scale_f32 v119, s[16:17], v22, v22, 1.0
	v_rcp_f32_e32 v127, v119
	v_mov_b32_e32 v179, v137
	v_pk_mul_f32 v[136:137], v[170:171], v[116:117] op_sel_hi:[0,1]
	v_fma_f32 v125, -v119, v127, 1.0
	v_fmac_f32_e32 v127, v125, v127
	v_div_scale_f32 v125, vcc, 1.0, v22, 1.0
	v_mul_f32_e32 v128, v125, v127
	v_fma_f32 v135, -v119, v128, v125
	v_fmac_f32_e32 v128, v135, v127
	v_fma_f32 v119, -v119, v128, v125
	v_div_fmas_f32 v119, v119, v127, v128
	v_div_fixup_f32 v22, v119, v22, 1.0
	v_pk_mul_f32 v[152:153], v[142:143], v[22:23] op_sel_hi:[1,0]
	v_pk_mul_f32 v[172:173], v[22:23], v[142:143] op_sel_hi:[0,1] neg_lo:[0,1] neg_hi:[0,1]
	v_pk_mul_f32 v[142:143], v[144:145], v[22:23] op_sel_hi:[1,0]
	v_pk_mul_f32 v[144:145], v[22:23], v[144:145] op_sel_hi:[0,1] neg_lo:[0,1] neg_hi:[0,1]
	v_cvt_f32_f16_e32 v22, v84
	v_cvt_f32_f16_sdwa v119, v84 dst_sel:DWORD dst_unused:UNUSED_PAD src0_sel:WORD_1
	v_cvt_f32_f16_e32 v125, v85
	v_cvt_f32_f16_sdwa v127, v85 dst_sel:DWORD dst_unused:UNUSED_PAD src0_sel:WORD_1
	v_mul_f32_e32 v22, 0xbfb8aa3b, v22
	v_pk_mul_f32 v[142:143], v[142:143], v[138:139]
	v_exp_f32_e32 v138, v22
	v_mul_f32_e32 v22, 0xbfb8aa3b, v119
	v_exp_f32_e32 v139, v22
	v_mul_f32_e32 v22, 0xbfb8aa3b, v125
	v_exp_f32_e32 v166, v22
	v_mul_f32_e32 v22, 0xbfb8aa3b, v127
	v_exp_f32_e32 v167, v22
	v_mov_b32_e32 v125, v118
	v_pk_mul_f32 v[118:119], v[112:113], v[110:111]
	v_pk_mul_f32 v[140:141], v[152:153], v[140:141]
	v_pk_mul_f32 v[152:153], v[42:43], v[122:123] op_sel_hi:[0,1] neg_lo:[0,1] neg_hi:[0,1]
	v_pk_mul_f32 v[154:155], v[42:43], v[124:125] op_sel_hi:[0,1] neg_lo:[0,1] neg_hi:[0,1]
	v_pk_mul_f32 v[122:123], v[114:115], v[110:111] op_sel:[0,1] op_sel_hi:[1,0]
	v_pk_mul_f32 v[158:159], v[166:167], v[144:145]
	v_pk_mul_f32 v[162:163], v[166:167], v[170:171]
	v_pk_mul_f32 v[166:167], v[166:167], v[108:109]
	v_pk_mul_f32 v[124:125], v[116:117], v[108:109]
	v_pk_fma_f32 v[108:109], v[112:113], v[172:173], 0 op_sel_hi:[1,0,0]
	v_mov_b32_e32 v119, v126
	v_pk_mul_f32 v[156:157], v[138:139], v[172:173]
	v_pk_mul_f32 v[160:161], v[138:139], v[168:169]
	v_pk_mul_f32 v[164:165], v[138:139], v[110:111]
	v_pk_mul_f32 v[138:139], v[140:141], v[104:105]
	v_pk_fma_f32 v[108:109], v[114:115], v[172:173], v[108:109] op_sel:[0,1,0]
	v_pk_add_f32 v[118:119], v[118:119], 0 op_sel_hi:[1,0]
	v_mov_b32_e32 v123, v129
	v_pk_fma_f32 v[108:109], v[116:117], v[144:145], v[108:109] op_sel_hi:[1,0,1]
	v_pk_add_f32 v[118:119], v[122:123], v[118:119]
	v_mov_b32_e32 v125, v134
	v_pk_mul_f32 v[134:135], v[168:169], v[112:113] op_sel_hi:[0,1]
	v_mov_b32_e32 v22, v169
	v_mov_b32_e32 v116, v138
	v_mov_b32_e32 v117, v130
	v_pk_mul_f32 v[176:177], v[142:143], v[106:107]
	v_pk_add_f32 v[118:119], v[124:125], v[118:119]
	v_pk_fma_f32 v[112:113], v[134:135], v[104:105], 0 op_sel_hi:[1,0,0]
	v_pk_mul_f32 v[124:125], v[22:23], v[114:115] op_sel_hi:[0,1]
	v_mov_b32_e32 v22, v171
	v_pk_add_f32 v[116:117], v[116:117], 0 op_sel_hi:[1,0]
	v_mov_b32_e32 v130, v139
	v_pk_fma_f32 v[108:109], v[120:121], v[144:145], v[108:109] op_sel:[0,1,0]
	v_pk_fma_f32 v[112:113], v[124:125], v[104:105], v[112:113] op_sel:[0,1,0]
	v_pk_mul_f32 v[126:127], v[22:23], v[120:121] op_sel_hi:[0,1]
	v_pk_add_f32 v[116:117], v[130:131], v[116:117]
	v_mov_b32_e32 v120, v176
	v_mov_b32_e32 v121, v132
	v_pk_fma_f32 v[112:113], v[136:137], v[106:107], v[112:113] op_sel_hi:[1,0,1]
	v_pk_add_f32 v[116:117], v[120:121], v[116:117]
	v_mov_b32_e32 v132, v177
	v_pk_add_f32 v[118:119], v[178:179], v[118:119]
	v_pk_fma_f32 v[112:113], v[126:127], v[106:107], v[112:113] op_sel:[0,1,0]
	v_pk_add_f32 v[116:117], v[132:133], v[116:117]
	v_mov_b32_dpp v110, v108 quad_perm:[1,0,3,2] row_mask:0xf bank_mask:0xf bound_ctrl:1
	v_mov_b32_dpp v111, v109 quad_perm:[1,0,3,2] row_mask:0xf bank_mask:0xf bound_ctrl:1
	v_mov_b32_dpp v122, v118 quad_perm:[1,0,3,2] row_mask:0xf bank_mask:0xf bound_ctrl:1
	v_mov_b32_dpp v123, v119 quad_perm:[1,0,3,2] row_mask:0xf bank_mask:0xf bound_ctrl:1
	v_mov_b32_dpp v114, v112 quad_perm:[1,0,3,2] row_mask:0xf bank_mask:0xf bound_ctrl:1
	v_mov_b32_dpp v115, v113 quad_perm:[1,0,3,2] row_mask:0xf bank_mask:0xf bound_ctrl:1
	v_mov_b32_dpp v120, v116 quad_perm:[1,0,3,2] row_mask:0xf bank_mask:0xf bound_ctrl:1
	v_mov_b32_dpp v121, v117 quad_perm:[1,0,3,2] row_mask:0xf bank_mask:0xf bound_ctrl:1
	v_pk_add_f32 v[108:109], v[108:109], v[110:111]
	v_pk_add_f32 v[118:119], v[118:119], v[122:123]
	v_pk_add_f32 v[112:113], v[112:113], v[114:115]
	v_pk_add_f32 v[116:117], v[116:117], v[120:121]
	v_mov_b32_dpp v110, v108 quad_perm:[2,3,0,1] row_mask:0xf bank_mask:0xf bound_ctrl:1
	v_mov_b32_dpp v111, v109 quad_perm:[2,3,0,1] row_mask:0xf bank_mask:0xf bound_ctrl:1
	v_mov_b32_dpp v122, v118 quad_perm:[2,3,0,1] row_mask:0xf bank_mask:0xf bound_ctrl:1
	v_mov_b32_dpp v123, v119 quad_perm:[2,3,0,1] row_mask:0xf bank_mask:0xf bound_ctrl:1
	v_mov_b32_dpp v114, v112 quad_perm:[2,3,0,1] row_mask:0xf bank_mask:0xf bound_ctrl:1
	v_mov_b32_dpp v115, v113 quad_perm:[2,3,0,1] row_mask:0xf bank_mask:0xf bound_ctrl:1
	v_mov_b32_dpp v120, v116 quad_perm:[2,3,0,1] row_mask:0xf bank_mask:0xf bound_ctrl:1
	v_mov_b32_dpp v121, v117 quad_perm:[2,3,0,1] row_mask:0xf bank_mask:0xf bound_ctrl:1
	v_pk_add_f32 v[108:109], v[108:109], v[110:111]
	v_pk_add_f32 v[118:119], v[118:119], v[122:123]
	v_pk_add_f32 v[112:113], v[112:113], v[114:115]
	v_pk_add_f32 v[116:117], v[116:117], v[120:121]
	v_mov_b32_dpp v110, v108 row_ror:4 row_mask:0xf bank_mask:0xf bound_ctrl:1
	v_mov_b32_dpp v111, v109 row_ror:4 row_mask:0xf bank_mask:0xf bound_ctrl:1
	v_mov_b32_dpp v122, v118 row_ror:4 row_mask:0xf bank_mask:0xf bound_ctrl:1
	v_mov_b32_dpp v123, v119 row_ror:4 row_mask:0xf bank_mask:0xf bound_ctrl:1
	v_mov_b32_dpp v114, v112 row_ror:4 row_mask:0xf bank_mask:0xf bound_ctrl:1
	v_mov_b32_dpp v115, v113 row_ror:4 row_mask:0xf bank_mask:0xf bound_ctrl:1
	v_mov_b32_dpp v120, v116 row_ror:4 row_mask:0xf bank_mask:0xf bound_ctrl:1
	v_mov_b32_dpp v121, v117 row_ror:4 row_mask:0xf bank_mask:0xf bound_ctrl:1
	v_pk_add_f32 v[108:109], v[108:109], v[110:111]
	v_pk_add_f32 v[118:119], v[118:119], v[122:123]
	v_pk_add_f32 v[112:113], v[112:113], v[114:115]
	v_pk_add_f32 v[116:117], v[116:117], v[120:121]
	v_mov_b32_e32 v128, v134
	v_mov_b32_e32 v129, v124
	v_mov_b32_e32 v130, v136
	v_mov_b32_e32 v131, v126
	v_mov_b32_e32 v124, v135
	v_mov_b32_e32 v126, v137
	v_mov_b32_dpp v110, v108 row_ror:8 row_mask:0xf bank_mask:0xf bound_ctrl:1
	v_mov_b32_dpp v111, v109 row_ror:8 row_mask:0xf bank_mask:0xf bound_ctrl:1
	v_mov_b32_dpp v122, v118 row_ror:8 row_mask:0xf bank_mask:0xf bound_ctrl:1
	v_mov_b32_dpp v123, v119 row_ror:8 row_mask:0xf bank_mask:0xf bound_ctrl:1
	v_mov_b32_dpp v114, v112 row_ror:8 row_mask:0xf bank_mask:0xf bound_ctrl:1
	v_mov_b32_dpp v115, v113 row_ror:8 row_mask:0xf bank_mask:0xf bound_ctrl:1
	v_mov_b32_dpp v120, v116 row_ror:8 row_mask:0xf bank_mask:0xf bound_ctrl:1
	v_mov_b32_dpp v121, v117 row_ror:8 row_mask:0xf bank_mask:0xf bound_ctrl:1
	ds_write_b128 v29, v[152:155] offset:19968
	ds_write_b128 v29, v[156:159] offset:20224
	ds_write_b128 v29, v[160:163] offset:20480
	ds_write_b128 v29, v[128:131] offset:20736
	ds_write_b128 v29, v[124:127] offset:20992
	ds_write_b128 v29, v[140:143] offset:21248
	ds_write_b128 v29, v[12:15] offset:21504
	ds_write_b128 v29, v[164:167] offset:21760
	v_pk_mul_f32 v[12:13], v[160:161], v[104:105]
	v_pk_mul_f32 v[14:15], v[162:163], v[106:107]
	ds_write_b128 v29, v[12:15] offset:22016
	s_and_saveexec_b64 s[16:17], s[12:13]
	s_cbranch_execnz .LBB0_1182
	s_or_b64 exec, exec, s[16:17]
	s_and_saveexec_b64 s[16:17], s[4:5]
	s_cbranch_execnz .LBB0_1183
